# P3 v13: v6 + state waves load the decay row once per step and broadcast it with DPP quad_perm (6 fewer vector loads per step)
# speedup vs baseline: 1.0024x; 1.0024x over previous
; #define LAS __attribute__((address_space(3)))
; __device__ __forceinline__ void gla_scan_item(const Ctx& C, int item, LAS unsigned char* lds, int tid) {
;     const int jx = item >> 3, bh = (item & 7) * 4 + (jx >> 3), sl = jx & 7, b = bh >> 2, h = bh & 3;
;     LAS bf16* Aq = (LAS bf16*)lds;
;     LAS bf16* Bc = (LAS bf16*)(lds + 25600);
;     LAS bf16* Kt = (LAS bf16*)(lds + 38400);
;     const int wave = tid >> 6, lane = tid & 63, l15 = lane & 15, quad = lane >> 4;
;     f32x4 S[2] = {(f32x4){0.f, 0.f, 0.f, 0.f}, (f32x4){0.f, 0.f, 0.f, 0.f}};
;     *(LAS u32x4*)(Bc + (tid >> 4) * 200 + (tid & 15) * 8) = (u32x4){0u, 0u, 0u, 0u};
;     u32x4 rq0A, rq1A, rsA, rk0A, rk1A, rvA = (u32x4){0u, 0u, 0u, 0u}; f32x4 rdA;
;     u32x4 rq0B, rq1B, rsB, rk0B, rk1B, rvB = (u32x4){0u, 0u, 0u, 0u}; f32x4 rdB;
.LBB0_428:
	s_cmp_lt_i32 s96, 4
	s_cselect_b64 s[4:5], -1, 0
	s_add_u32 s6, s94, 0xb300000
	s_addc_u32 s7, s95, 0
	s_and_b64 s[0:1], s[4:5], s[0:1]
	s_andn2_b64 vcc, exec, s[0:1]
	s_cbranch_vccnz .LBB0_496
	s_cmpk_gt_i32 s2, 0xff
	s_cbranch_scc1 .LBB0_496
	v_readfirstlane_b32 s32, v163
	v_and_b32_e32 v203, 63, v162
	v_and_b32_e32 v202, 15, v162
	v_bfe_u32 v201, v162, 4, 2
	v_lshrrev_b32_e32 v200, 4, v203
	v_lshl_add_u32 v200, v163, 3, v200
	v_and_b32_e32 v199, 15, v200
	v_xor_b32_e32 v199, v199, v202
	v_lshlrev_b32_e32 v255, 10, v200
	v_lshl_add_u32 v255, v199, 4, v255
	v_lshrrev_b32_e32 v200, 4, v203
	v_lshl_add_u32 v200, v163, 3, v200
	v_add_u32_e32 v200, 4, v200
	v_and_b32_e32 v199, 15, v200
	v_xor_b32_e32 v199, v199, v202
	v_lshlrev_b32_e32 v254, 10, v200
	v_lshl_add_u32 v254, v199, 4, v254
	v_lshrrev_b32_e32 v200, 3, v203
	v_lshl_add_u32 v200, v163, 3, v200
	v_bfe_u32 v199, v200, 1, 3
	v_and_b32_e32 v198, 7, v203
	v_xor_b32_e32 v199, v199, v198
	v_lshlrev_b32_e32 v253, 7, v200
	v_lshl_add_u32 v253, v199, 4, v253
	v_lshrrev_b32_e32 v200, 3, v203
	v_lshl_add_u32 v200, v163, 4, v200
	v_bfe_u32 v199, v200, 1, 3
	v_and_b32_e32 v198, 7, v203
	v_xor_b32_e32 v199, v199, v198
	v_lshlrev_b32_e32 v252, 7, v200
	v_lshl_add_u32 v252, v199, 4, v252
	v_lshrrev_b32_e32 v200, 3, v203
	v_lshl_add_u32 v200, v163, 4, v200
	v_add_u32_e32 v200, 8, v200
	v_bfe_u32 v199, v200, 1, 3
	v_and_b32_e32 v198, 7, v203
	v_xor_b32_e32 v199, v199, v198
	v_lshlrev_b32_e32 v251, 7, v200
	v_lshl_add_u32 v251, v199, 4, v251
	s_lshl_b32 s46, s32, 11
	s_lshl_b32 s47, s32, 10
	s_add_i32 s47, s47, 0x4000
	s_add_i32 s48, s46, 0x6000
	v_and_b32_e32 v200, 1, v163
	v_lshl_add_u32 v200, v200, 5, v202
	v_or_b32_e32 v199, 0, v201
	v_and_b32_e32 v198, 15, v200
	v_xor_b32_e32 v199, v199, v198
	v_lshlrev_b32_e32 v241, 8, v200
	v_lshl_add_u32 v241, v199, 4, v241
	v_or_b32_e32 v199, 4, v201
	v_and_b32_e32 v198, 15, v200
	v_xor_b32_e32 v199, v199, v198
	v_lshlrev_b32_e32 v240, 8, v200
	v_lshl_add_u32 v240, v199, 4, v240
	v_or_b32_e32 v199, 8, v201
	v_and_b32_e32 v198, 15, v200
	v_xor_b32_e32 v199, v199, v198
	v_lshlrev_b32_e32 v239, 8, v200
	v_lshl_add_u32 v239, v199, 4, v239
	v_or_b32_e32 v199, 12, v201
	v_and_b32_e32 v198, 15, v200
	v_xor_b32_e32 v199, v199, v198
	v_lshlrev_b32_e32 v238, 8, v200
	v_lshl_add_u32 v238, v199, 4, v238
	v_or_b32_e32 v199, 0, v201
	v_bfe_u32 v198, v200, 1, 3
	v_xor_b32_e32 v199, v199, v198
	v_lshlrev_b32_e32 v231, 7, v200
	v_lshl_add_u32 v231, v199, 4, v231
	v_add_u32_e32 v231, 0x4000, v231
	v_or_b32_e32 v199, 4, v201
	v_bfe_u32 v198, v200, 1, 3
	v_xor_b32_e32 v199, v199, v198
	v_lshlrev_b32_e32 v230, 7, v200
	v_lshl_add_u32 v230, v199, 4, v230
	v_add_u32_e32 v230, 0x4000, v230
	v_lshlrev_b32_e32 v248, 11, v200
	v_lshl_add_u32 v248, v201, 3, v248
	v_add_u32_e32 v247, 0x8000, v248
	v_or_b32_e32 v199, 0, v201
	v_and_b32_e32 v198, 15, v202
	v_xor_b32_e32 v199, v199, v198
	v_lshlrev_b32_e32 v223, 8, v202
	v_lshl_add_u32 v223, v199, 4, v223
	v_add_u32_e32 v223, 0x1e000, v223
	v_or_b32_e32 v199, 4, v201
	v_and_b32_e32 v198, 15, v202
	v_xor_b32_e32 v199, v199, v198
	v_lshlrev_b32_e32 v222, 8, v202
	v_lshl_add_u32 v222, v199, 4, v222
	v_add_u32_e32 v222, 0x1e000, v222
	v_or_b32_e32 v199, 8, v201
	v_and_b32_e32 v198, 15, v202
	v_xor_b32_e32 v199, v199, v198
	v_lshlrev_b32_e32 v221, 8, v202
	v_lshl_add_u32 v221, v199, 4, v221
	v_add_u32_e32 v221, 0x1e000, v221
	v_or_b32_e32 v199, 12, v201
	v_and_b32_e32 v198, 15, v202
	v_xor_b32_e32 v199, v199, v198
	v_lshlrev_b32_e32 v220, 8, v202
	v_lshl_add_u32 v220, v199, 4, v220
	v_add_u32_e32 v220, 0x1e000, v220
	v_or_b32_e32 v199, 0, v201
	v_bfe_u32 v198, v202, 1, 3
	v_xor_b32_e32 v199, v199, v198
	v_lshlrev_b32_e32 v219, 7, v202
	v_lshl_add_u32 v219, v199, 4, v219
	v_add_u32_e32 v219, 0x20100, v219
	v_or_b32_e32 v199, 4, v201
	v_bfe_u32 v198, v202, 1, 3
	v_xor_b32_e32 v199, v199, v198
	v_lshlrev_b32_e32 v218, 7, v202
	v_lshl_add_u32 v218, v199, 4, v218
	v_add_u32_e32 v218, 0x20100, v218
	v_and_b32_e32 v200, 1, v163
	v_lshl_add_u32 v200, v200, 6, v202
	v_or_b32_e32 v199, 0, v201
	v_bfe_u32 v198, v200, 1, 3
	v_xor_b32_e32 v199, v199, v198
	v_lshlrev_b32_e32 v227, 7, v200
	v_lshl_add_u32 v227, v199, 4, v227
	v_add_u32_e32 v227, 0x6000, v227
	v_or_b32_e32 v199, 4, v201
	v_bfe_u32 v198, v200, 1, 3
	v_xor_b32_e32 v199, v199, v198
	v_lshlrev_b32_e32 v226, 7, v200
	v_lshl_add_u32 v226, v199, 4, v226
	v_add_u32_e32 v226, 0x6000, v226
	v_or_b32_e32 v199, 0, v201
	v_bfe_u32 v198, v202, 1, 3
	v_xor_b32_e32 v199, v199, v198
	v_lshlrev_b32_e32 v217, 7, v202
	v_lshl_add_u32 v217, v199, 4, v217
	v_add_u32_e32 v217, 0x20100, v217
	v_or_b32_e32 v199, 4, v201
	v_bfe_u32 v198, v202, 1, 3
	v_xor_b32_e32 v199, v199, v198
	v_lshlrev_b32_e32 v216, 7, v202
	v_lshl_add_u32 v216, v199, 4, v216
	v_add_u32_e32 v216, 0x20100, v216
	v_add_u32_e32 v235, 0x14000, v241
	v_add_u32_e32 v234, 0x14000, v240
	v_add_u32_e32 v233, 0x14000, v239
	v_add_u32_e32 v232, 0x14000, v238
	v_add_u32_e32 v229, 0x14000, v231
	v_add_u32_e32 v228, 0x14000, v230
	v_add_u32_e32 v225, 0x14000, v227
	v_add_u32_e32 v224, 0x14000, v226
	v_and_b32_e32 v200, 1, v163
	v_lshrrev_b32_e32 v199, 1, v201
	v_lshl_add_u32 v199, v200, 3, v199
	v_xor_b32_e32 v199, v199, v202
	v_lshlrev_b32_e32 v215, 8, v202
	v_lshl_add_u32 v215, v199, 4, v215
	v_and_b32_e32 v199, 1, v201
	v_lshl_add_u32 v215, v199, 3, v215
	v_add_u32_e32 v215, 0x1e000, v215
	v_and_b32_e32 v200, 1, v163
	v_lshrrev_b32_e32 v199, 1, v201
	v_lshl_add_u32 v199, v200, 3, v199
	v_add_u32_e32 v199, 2, v199
	v_xor_b32_e32 v199, v199, v202
	v_lshlrev_b32_e32 v214, 8, v202
	v_lshl_add_u32 v214, v199, 4, v214
	v_and_b32_e32 v199, 1, v201
	v_lshl_add_u32 v214, v199, 3, v214
	v_add_u32_e32 v214, 0x1e000, v214
	v_and_b32_e32 v200, 1, v163
	v_lshrrev_b32_e32 v199, 1, v201
	v_lshl_add_u32 v199, v200, 3, v199
	v_add_u32_e32 v199, 4, v199
	v_xor_b32_e32 v199, v199, v202
	v_lshlrev_b32_e32 v213, 8, v202
	v_lshl_add_u32 v213, v199, 4, v213
	v_and_b32_e32 v199, 1, v201
	v_lshl_add_u32 v213, v199, 3, v213
	v_add_u32_e32 v213, 0x1e000, v213
	v_and_b32_e32 v200, 1, v163
	v_lshrrev_b32_e32 v199, 1, v201
	v_lshl_add_u32 v199, v200, 3, v199
	v_add_u32_e32 v199, 6, v199
	v_xor_b32_e32 v199, v199, v202
	v_lshlrev_b32_e32 v212, 8, v202
	v_lshl_add_u32 v212, v199, 4, v212
	v_and_b32_e32 v199, 1, v201
	v_lshl_add_u32 v212, v199, 3, v212
	v_add_u32_e32 v212, 0x1e000, v212
	v_bfe_u32 v200, v162, 2, 6
	v_and_b32_e32 v198, 3, v162
	v_lshl_add_u32 v199, v198, 3, 0
	v_lshlrev_b32_e32 v211, 7, v199
	v_bfe_u32 v199, v199, 1, 3
	v_lshrrev_b32_e32 v246, 3, v200
	v_xor_b32_e32 v199, v199, v246
	v_lshl_add_u32 v211, v199, 4, v211
	v_and_b32_e32 v199, 7, v200
	v_lshl_add_u32 v211, v199, 1, v211
	v_add_u32_e32 v211, 0x20100, v211
	v_lshl_add_u32 v199, v198, 3, 1
	v_lshlrev_b32_e32 v210, 7, v199
	v_bfe_u32 v199, v199, 1, 3
	v_lshrrev_b32_e32 v246, 3, v200
	v_xor_b32_e32 v199, v199, v246
	v_lshl_add_u32 v210, v199, 4, v210
	v_and_b32_e32 v199, 7, v200
	v_lshl_add_u32 v210, v199, 1, v210
	v_add_u32_e32 v210, 0x20100, v210
	v_lshl_add_u32 v199, v198, 3, 2
	v_lshlrev_b32_e32 v209, 7, v199
	v_bfe_u32 v199, v199, 1, 3
	v_lshrrev_b32_e32 v246, 3, v200
	v_xor_b32_e32 v199, v199, v246
	v_lshl_add_u32 v209, v199, 4, v209
	v_and_b32_e32 v199, 7, v200
	v_lshl_add_u32 v209, v199, 1, v209
	v_add_u32_e32 v209, 0x20100, v209
	v_lshl_add_u32 v199, v198, 3, 3
	v_lshlrev_b32_e32 v208, 7, v199
	v_bfe_u32 v199, v199, 1, 3
	v_lshrrev_b32_e32 v246, 3, v200
	v_xor_b32_e32 v199, v199, v246
	v_lshl_add_u32 v208, v199, 4, v208
	v_and_b32_e32 v199, 7, v200
	v_lshl_add_u32 v208, v199, 1, v208
	v_add_u32_e32 v208, 0x20100, v208
	v_lshl_add_u32 v199, v198, 3, 4
	v_lshlrev_b32_e32 v207, 7, v199
	v_bfe_u32 v199, v199, 1, 3
	v_lshrrev_b32_e32 v246, 3, v200
	v_xor_b32_e32 v199, v199, v246
	v_lshl_add_u32 v207, v199, 4, v207
	v_and_b32_e32 v199, 7, v200
	v_lshl_add_u32 v207, v199, 1, v207
	v_add_u32_e32 v207, 0x20100, v207
	v_lshl_add_u32 v199, v198, 3, 5
	v_lshlrev_b32_e32 v206, 7, v199
	v_bfe_u32 v199, v199, 1, 3
	v_lshrrev_b32_e32 v246, 3, v200
	v_xor_b32_e32 v199, v199, v246
	v_lshl_add_u32 v206, v199, 4, v206
	v_and_b32_e32 v199, 7, v200
	v_lshl_add_u32 v206, v199, 1, v206
	v_add_u32_e32 v206, 0x20100, v206
	v_lshl_add_u32 v199, v198, 3, 6
	v_lshlrev_b32_e32 v205, 7, v199
	v_bfe_u32 v199, v199, 1, 3
	v_lshrrev_b32_e32 v246, 3, v200
	v_xor_b32_e32 v199, v199, v246
	v_lshl_add_u32 v205, v199, 4, v205
	v_and_b32_e32 v199, 7, v200
	v_lshl_add_u32 v205, v199, 1, v205
	v_add_u32_e32 v205, 0x20100, v205
	v_lshl_add_u32 v199, v198, 3, 7
	v_lshlrev_b32_e32 v204, 7, v199
	v_bfe_u32 v199, v199, 1, 3
	v_lshrrev_b32_e32 v246, 3, v200
	v_xor_b32_e32 v199, v199, v246
	v_lshl_add_u32 v204, v199, 4, v204
	v_and_b32_e32 v199, 7, v200
	v_lshl_add_u32 v204, v199, 1, v204
	v_add_u32_e32 v204, 0x20100, v204
	v_bfe_u32 v200, v162, 2, 6
	v_and_b32_e32 v199, 3, v162
	v_lshlrev_b32_e32 v250, 14, v200
	v_lshl_add_u32 v250, v199, 4, v250
	v_and_b32_e32 v200, 1, v163
	v_lshlrev_b32_e32 v249, 8, v200
	v_lshl_add_u32 v249, v201, 4, v249
	v_and_b32_e32 v199, 3, v202
	v_lshl_add_u32 v249, v199, 6, v249
	v_lshlrev_b32_e32 v245, 16, v200
	v_lshl_add_u32 v245, v201, 12, v245
	v_lshl_add_u32 v245, v202, 2, v245
	v_add_u32_e32 v244, 0x4000, v245
	v_add_u32_e32 v243, 0x8000, v245
	v_add_u32_e32 v242, 0xc000, v245
	v_lshlrev_b32_e32 v246, 4, v162
	v_add_u32_e32 v246, 0x1e000, v246
	v_mov_b32_e32 v8, 0
	v_mov_b32_e32 v9, 0
	v_mov_b32_e32 v10, 0
	v_mov_b32_e32 v11, 0
	s_cmp_gt_u32 s32, 3
	s_cbranch_scc1 .Lp3V_entry
	s_cmp_gt_u32 s32, 1
	s_cbranch_scc1 .Lp3S_entry

; #define LAS __attribute__((address_space(3)))
; __device__ __forceinline__ void gla_scan_item(const Ctx& C, int item, LAS unsigned char* lds, int tid) {
;     const int jx = item >> 3, bh = (item & 7) * 4 + (jx >> 3), sl = jx & 7, b = bh >> 2, h = bh & 3;
;     LAS bf16* Aq = (LAS bf16*)lds;
;     LAS bf16* Bc = (LAS bf16*)(lds + 25600);
;     LAS bf16* Kt = (LAS bf16*)(lds + 38400);
;     const int wave = tid >> 6, lane = tid & 63, l15 = lane & 15, quad = lane >> 4;
;     f32x4 S[2] = {(f32x4){0.f, 0.f, 0.f, 0.f}, (f32x4){0.f, 0.f, 0.f, 0.f}};
;     *(LAS u32x4*)(Bc + (tid >> 4) * 200 + (tid & 15) * 8) = (u32x4){0u, 0u, 0u, 0u};
;     u32x4 rq0A, rq1A, rsA, rk0A, rk1A, rvA = (u32x4){0u, 0u, 0u, 0u}; f32x4 rdA;
;     u32x4 rq0B, rq1B, rsB, rk0B, rk1B, rvB = (u32x4){0u, 0u, 0u, 0u}; f32x4 rdB;
.Lp3S_item:
	s_lshr_b32 s4, s3, 3
	s_and_b32 s41, s4, 7
	s_lshr_b32 s5, s4, 3
	s_and_b32 s37, s3, 7
	s_lshl_b32 s37, s37, 2
	s_add_i32 s37, s37, s5
	s_lshr_b32 s39, s37, 2
	s_and_b32 s40, s37, 3
	s_add_u32 s8, s94, 0x1d800000
	s_addc_u32 s9, s95, 0
	s_lshl_b32 s31, s39, 21
	s_add_u32 s8, s8, s31
	s_addc_u32 s9, s9, 0
	s_lshl_b32 s31, s40, 8
	s_add_u32 s8, s8, s31
	s_addc_u32 s9, s9, 0
	s_add_u32 s10, s94, 0x2f00000
	s_addc_u32 s11, s95, 0
	s_lshl_b32 s31, s37, 18
	s_add_u32 s10, s10, s31
	s_addc_u32 s11, s11, 0
	s_add_u32 s12, s94, 0x3700000
	s_addc_u32 s13, s95, 0
	s_lshl_b32 s31, s37, 19
	s_add_u32 s12, s12, s31
	s_addc_u32 s13, s13, 0
	s_add_u32 s16, s94, 0x2e00000
	s_addc_u32 s17, s95, 0
	s_lshl_b32 s31, s37, 14
	s_add_u32 s16, s16, s31
	s_addc_u32 s17, s17, 0
	s_add_u32 s34, s92, 0x4090000
	s_addc_u32 s35, s93, 0
	s_lshl_b32 s31, s37, 17
	s_add_u32 s34, s34, s31
	s_addc_u32 s35, s35, 0
	s_lshl_b32 s31, s41, 7
	s_add_u32 s34, s34, s31
	s_addc_u32 s35, s35, 0
	v_mov_b32_e32 v60, 0
	v_mov_b32_e32 v61, 0
	v_mov_b32_e32 v62, 0
	v_mov_b32_e32 v63, 0
	v_mov_b32_e32 v64, 0
	v_mov_b32_e32 v65, 0
	v_mov_b32_e32 v66, 0
	v_mov_b32_e32 v67, 0
	v_mov_b32_e32 v68, 0
	v_mov_b32_e32 v69, 0
	v_mov_b32_e32 v70, 0
	v_mov_b32_e32 v71, 0
	v_mov_b32_e32 v72, 0
	v_mov_b32_e32 v73, 0
	v_mov_b32_e32 v74, 0
	v_mov_b32_e32 v75, 0
	v_mov_b32_e32 v76, 0
	v_mov_b32_e32 v77, 0
	v_mov_b32_e32 v78, 0
	v_mov_b32_e32 v79, 0
	v_mov_b32_e32 v80, 0
	v_mov_b32_e32 v81, 0
	v_mov_b32_e32 v82, 0
	v_mov_b32_e32 v83, 0
	v_mov_b32_e32 v84, 0
	v_mov_b32_e32 v85, 0
	v_mov_b32_e32 v86, 0
	v_mov_b32_e32 v87, 0
	v_mov_b32_e32 v88, 0
	v_mov_b32_e32 v89, 0
	v_mov_b32_e32 v90, 0
	v_mov_b32_e32 v91, 0
	ds_write_b128 v246, v[8:11]
	s_mov_b32 m0, s46
	s_nop 0
	global_load_lds_dwordx4 v255, s[8:9]
	s_add_i32 m0, s46, 0x400
	s_nop 0
	global_load_lds_dwordx4 v254, s[8:9]
	s_mov_b32 m0, s47
	s_nop 0
	global_load_lds_dwordx4 v253, s[10:11]
	s_mov_b32 m0, s48
	s_nop 0
	global_load_lds_dwordx4 v252, s[12:13]
	s_add_i32 m0, s48, 0x400
	s_nop 0
	global_load_lds_dwordx4 v251, s[12:13]
	s_add_u32 s8, s8, 0x10000
	s_addc_u32 s9, s9, 0
	s_add_u32 s10, s10, 0x2000
	s_addc_u32 s11, s11, 0
	s_add_u32 s12, s12, 0x4000
	s_addc_u32 s13, s13, 0
	s_add_i32 m0, s46, 0xa000
	s_nop 0
	global_load_lds_dwordx4 v255, s[8:9]
	s_add_i32 m0, s46, 0xa400
	s_nop 0
	global_load_lds_dwordx4 v254, s[8:9]
	s_add_i32 m0, s47, 0xa000
	s_nop 0
	global_load_lds_dwordx4 v253, s[10:11]
	s_add_i32 m0, s48, 0xa000
	s_nop 0
	global_load_lds_dwordx4 v252, s[12:13]
	s_add_i32 m0, s48, 0xa400
	s_nop 0
	global_load_lds_dwordx4 v251, s[12:13]
	s_add_u32 s8, s8, 0x10000
	s_addc_u32 s9, s9, 0
	s_add_u32 s10, s10, 0x2000
	s_addc_u32 s11, s11, 0
	s_add_u32 s12, s12, 0x4000
	s_addc_u32 s13, s13, 0
	global_load_dwordx4 v[92:95], v249, s[16:17]
	s_add_u32 s16, s16, 0x200
	s_addc_u32 s17, s17, 0
	global_load_dwordx4 v[108:111], v249, s[16:17]
	s_add_u32 s16, s16, 0x200
	s_addc_u32 s17, s17, 0
	global_load_dwordx4 v[124:127], v249, s[16:17]
	s_add_u32 s16, s16, 0x200
	s_addc_u32 s17, s17, 0
	s_waitcnt vmcnt(0)
	s_mov_b32 s33, 0
	s_waitcnt lgkmcnt(0)
	s_barrier
.Lp3S_loop:
	ds_read_b128 v[44:47], v217 offset:0
	ds_read_b128 v[48:51], v217 offset:2048
	ds_read_b128 v[12:15], v227 offset:0
	ds_read_b128 v[16:19], v227 offset:2048
	ds_read_b128 v[20:23], v227 offset:4096
	ds_read_b128 v[24:27], v227 offset:6144
	ds_read_b128 v[52:55], v216 offset:0
	ds_read_b128 v[56:59], v216 offset:2048
	ds_read_b128 v[28:31], v226 offset:0
	ds_read_b128 v[32:35], v226 offset:2048
	ds_read_b128 v[36:39], v226 offset:4096
	ds_read_b128 v[40:43], v226 offset:6144
	s_waitcnt vmcnt(12)
	v_mov_b32_dpp v96, v92 quad_perm:[0,0,0,0] row_mask:0xf bank_mask:0xf
	v_mov_b32_dpp v97, v93 quad_perm:[0,0,0,0] row_mask:0xf bank_mask:0xf
	v_mov_b32_dpp v98, v94 quad_perm:[0,0,0,0] row_mask:0xf bank_mask:0xf
	v_mov_b32_dpp v99, v95 quad_perm:[0,0,0,0] row_mask:0xf bank_mask:0xf
	v_mov_b32_dpp v100, v92 quad_perm:[1,1,1,1] row_mask:0xf bank_mask:0xf
	v_mov_b32_dpp v101, v93 quad_perm:[1,1,1,1] row_mask:0xf bank_mask:0xf
	v_mov_b32_dpp v102, v94 quad_perm:[1,1,1,1] row_mask:0xf bank_mask:0xf
	v_mov_b32_dpp v103, v95 quad_perm:[1,1,1,1] row_mask:0xf bank_mask:0xf
	v_mov_b32_dpp v104, v92 quad_perm:[2,2,2,2] row_mask:0xf bank_mask:0xf
	v_mov_b32_dpp v105, v93 quad_perm:[2,2,2,2] row_mask:0xf bank_mask:0xf
	v_mov_b32_dpp v106, v94 quad_perm:[2,2,2,2] row_mask:0xf bank_mask:0xf
	v_mov_b32_dpp v107, v95 quad_perm:[2,2,2,2] row_mask:0xf bank_mask:0xf
	v_mov_b32_dpp v112, v92 quad_perm:[3,3,3,3] row_mask:0xf bank_mask:0xf
	v_mov_b32_dpp v113, v93 quad_perm:[3,3,3,3] row_mask:0xf bank_mask:0xf
	v_mov_b32_dpp v114, v94 quad_perm:[3,3,3,3] row_mask:0xf bank_mask:0xf
	v_mov_b32_dpp v115, v95 quad_perm:[3,3,3,3] row_mask:0xf bank_mask:0xf
	v_pk_mul_f32 v[60:61], v[60:61], v[96:97]
	v_pk_mul_f32 v[62:63], v[62:63], v[98:99]
	v_pk_mul_f32 v[64:65], v[64:65], v[96:97]
	v_pk_mul_f32 v[66:67], v[66:67], v[98:99]
	v_pk_mul_f32 v[68:69], v[68:69], v[100:101]
	v_pk_mul_f32 v[70:71], v[70:71], v[102:103]
	v_pk_mul_f32 v[72:73], v[72:73], v[100:101]
	v_pk_mul_f32 v[74:75], v[74:75], v[102:103]
	v_pk_mul_f32 v[76:77], v[76:77], v[104:105]
	v_pk_mul_f32 v[78:79], v[78:79], v[106:107]
	v_pk_mul_f32 v[80:81], v[80:81], v[104:105]
	v_pk_mul_f32 v[82:83], v[82:83], v[106:107]
	v_pk_mul_f32 v[84:85], v[84:85], v[112:113]
	v_pk_mul_f32 v[86:87], v[86:87], v[114:115]
	v_pk_mul_f32 v[88:89], v[88:89], v[112:113]
	v_pk_mul_f32 v[90:91], v[90:91], v[114:115]
	s_add_i32 m0, s46, 0x14000
	s_nop 0
	global_load_lds_dwordx4 v255, s[8:9]
	s_add_i32 m0, s46, 0x14400
	s_nop 0
	global_load_lds_dwordx4 v254, s[8:9]
	s_add_i32 m0, s47, 0x14000
	s_nop 0
	global_load_lds_dwordx4 v253, s[10:11]
	s_add_i32 m0, s48, 0x14000
	s_nop 0
	global_load_lds_dwordx4 v252, s[12:13]
	s_add_i32 m0, s48, 0x14400
	s_nop 0
	global_load_lds_dwordx4 v251, s[12:13]
	s_cmp_lt_u32 s33, 29
	s_cselect_b32 s43, 0x10000, 0
	s_add_u32 s8, s8, s43
	s_addc_u32 s9, s9, 0
	s_cmp_lt_u32 s33, 29
	s_cselect_b32 s43, 0x2000, 0
	s_add_u32 s10, s10, s43
	s_addc_u32 s11, s11, 0
	s_cmp_lt_u32 s33, 29
	s_cselect_b32 s43, 0x4000, 0
	s_add_u32 s12, s12, s43
	s_addc_u32 s13, s13, 0
	s_waitcnt lgkmcnt(6)
	v_mfma_f32_16x16x32_bf16 v[60:63], v[12:15], v[44:47], v[60:63]
	v_mfma_f32_16x16x32_bf16 v[64:67], v[12:15], v[48:51], v[64:67]
	v_mfma_f32_16x16x32_bf16 v[68:71], v[16:19], v[44:47], v[68:71]
	v_mfma_f32_16x16x32_bf16 v[72:75], v[16:19], v[48:51], v[72:75]
	v_mfma_f32_16x16x32_bf16 v[76:79], v[20:23], v[44:47], v[76:79]
	v_mfma_f32_16x16x32_bf16 v[80:83], v[20:23], v[48:51], v[80:83]
	v_mfma_f32_16x16x32_bf16 v[84:87], v[24:27], v[44:47], v[84:87]
	v_mfma_f32_16x16x32_bf16 v[88:91], v[24:27], v[48:51], v[88:91]
	s_waitcnt lgkmcnt(0)
	v_mfma_f32_16x16x32_bf16 v[60:63], v[28:31], v[52:55], v[60:63]
	v_mfma_f32_16x16x32_bf16 v[64:67], v[28:31], v[56:59], v[64:67]
	v_mfma_f32_16x16x32_bf16 v[68:71], v[32:35], v[52:55], v[68:71]
	v_mfma_f32_16x16x32_bf16 v[72:75], v[32:35], v[56:59], v[72:75]
	v_mfma_f32_16x16x32_bf16 v[76:79], v[36:39], v[52:55], v[76:79]
	v_mfma_f32_16x16x32_bf16 v[80:83], v[36:39], v[56:59], v[80:83]
	v_mfma_f32_16x16x32_bf16 v[84:87], v[40:43], v[52:55], v[84:87]
	v_mfma_f32_16x16x32_bf16 v[88:91], v[40:43], v[56:59], v[88:91]
	s_nop 3
	global_load_dwordx4 v[92:95], v249, s[16:17]
	s_cmp_lt_u32 s33, 28
	s_cselect_b32 s43, 0x200, 0
	s_add_u32 s16, s16, s43
	s_addc_u32 s17, s17, 0
	s_add_i32 s33, s33, 1
	s_nop 7
	s_nop 7
	v_cvt_pk_bf16_f32 v140, v60, v61
	v_cvt_pk_bf16_f32 v141, v62, v63
	ds_write_b64 v215, v[140:141] offset:12544
	v_cvt_pk_bf16_f32 v144, v64, v65
	v_cvt_pk_bf16_f32 v145, v66, v67
	ds_write_b64 v215, v[144:145] offset:16640
	s_nop 1
	v_cvt_pk_bf16_f32 v140, v68, v69
	v_cvt_pk_bf16_f32 v141, v70, v71
	ds_write_b64 v214, v[140:141] offset:12544
	v_cvt_pk_bf16_f32 v144, v72, v73
	v_cvt_pk_bf16_f32 v145, v74, v75
	ds_write_b64 v214, v[144:145] offset:16640
	s_nop 1
	v_cvt_pk_bf16_f32 v140, v76, v77
	v_cvt_pk_bf16_f32 v141, v78, v79
	ds_write_b64 v213, v[140:141] offset:12544
	v_cvt_pk_bf16_f32 v144, v80, v81
	v_cvt_pk_bf16_f32 v145, v82, v83
	ds_write_b64 v213, v[144:145] offset:16640
	s_nop 1
	v_cvt_pk_bf16_f32 v140, v84, v85
	v_cvt_pk_bf16_f32 v141, v86, v87
	ds_write_b64 v212, v[140:141] offset:12544
	v_cvt_pk_bf16_f32 v144, v88, v89
	v_cvt_pk_bf16_f32 v145, v90, v91
	ds_write_b64 v212, v[144:145] offset:16640
	s_nop 1
	s_waitcnt vmcnt(7)
	s_waitcnt lgkmcnt(0)
	s_barrier
	ds_read_b128 v[44:47], v217 offset:12288
	ds_read_b128 v[48:51], v217 offset:14336
	ds_read_b128 v[12:15], v227 offset:40960
	ds_read_b128 v[16:19], v227 offset:43008
	ds_read_b128 v[20:23], v227 offset:45056
	ds_read_b128 v[24:27], v227 offset:47104
	ds_read_b128 v[52:55], v216 offset:12288
	ds_read_b128 v[56:59], v216 offset:14336
	ds_read_b128 v[28:31], v226 offset:40960
	ds_read_b128 v[32:35], v226 offset:43008
	ds_read_b128 v[36:39], v226 offset:45056
	ds_read_b128 v[40:43], v226 offset:47104
	s_waitcnt vmcnt(12)
	v_mov_b32_dpp v96, v108 quad_perm:[0,0,0,0] row_mask:0xf bank_mask:0xf
	v_mov_b32_dpp v97, v109 quad_perm:[0,0,0,0] row_mask:0xf bank_mask:0xf
	v_mov_b32_dpp v98, v110 quad_perm:[0,0,0,0] row_mask:0xf bank_mask:0xf
	v_mov_b32_dpp v99, v111 quad_perm:[0,0,0,0] row_mask:0xf bank_mask:0xf
	v_mov_b32_dpp v100, v108 quad_perm:[1,1,1,1] row_mask:0xf bank_mask:0xf
	v_mov_b32_dpp v101, v109 quad_perm:[1,1,1,1] row_mask:0xf bank_mask:0xf
	v_mov_b32_dpp v102, v110 quad_perm:[1,1,1,1] row_mask:0xf bank_mask:0xf
	v_mov_b32_dpp v103, v111 quad_perm:[1,1,1,1] row_mask:0xf bank_mask:0xf
	v_mov_b32_dpp v104, v108 quad_perm:[2,2,2,2] row_mask:0xf bank_mask:0xf
	v_mov_b32_dpp v105, v109 quad_perm:[2,2,2,2] row_mask:0xf bank_mask:0xf
	v_mov_b32_dpp v106, v110 quad_perm:[2,2,2,2] row_mask:0xf bank_mask:0xf
	v_mov_b32_dpp v107, v111 quad_perm:[2,2,2,2] row_mask:0xf bank_mask:0xf
	v_mov_b32_dpp v112, v108 quad_perm:[3,3,3,3] row_mask:0xf bank_mask:0xf
	v_mov_b32_dpp v113, v109 quad_perm:[3,3,3,3] row_mask:0xf bank_mask:0xf
	v_mov_b32_dpp v114, v110 quad_perm:[3,3,3,3] row_mask:0xf bank_mask:0xf
	v_mov_b32_dpp v115, v111 quad_perm:[3,3,3,3] row_mask:0xf bank_mask:0xf
	v_pk_mul_f32 v[60:61], v[60:61], v[96:97]
	v_pk_mul_f32 v[62:63], v[62:63], v[98:99]
	v_pk_mul_f32 v[64:65], v[64:65], v[96:97]
	v_pk_mul_f32 v[66:67], v[66:67], v[98:99]
	v_pk_mul_f32 v[68:69], v[68:69], v[100:101]
	v_pk_mul_f32 v[70:71], v[70:71], v[102:103]
	v_pk_mul_f32 v[72:73], v[72:73], v[100:101]
	v_pk_mul_f32 v[74:75], v[74:75], v[102:103]
	v_pk_mul_f32 v[76:77], v[76:77], v[104:105]
	v_pk_mul_f32 v[78:79], v[78:79], v[106:107]
	v_pk_mul_f32 v[80:81], v[80:81], v[104:105]
	v_pk_mul_f32 v[82:83], v[82:83], v[106:107]
	v_pk_mul_f32 v[84:85], v[84:85], v[112:113]
	v_pk_mul_f32 v[86:87], v[86:87], v[114:115]
	v_pk_mul_f32 v[88:89], v[88:89], v[112:113]
	v_pk_mul_f32 v[90:91], v[90:91], v[114:115]
	s_mov_b32 m0, s46
	s_nop 0
	global_load_lds_dwordx4 v255, s[8:9]
	s_add_i32 m0, s46, 0x400
	s_nop 0
	global_load_lds_dwordx4 v254, s[8:9]
	s_mov_b32 m0, s47
	s_nop 0
	global_load_lds_dwordx4 v253, s[10:11]
	s_mov_b32 m0, s48
	s_nop 0
	global_load_lds_dwordx4 v252, s[12:13]
	s_add_i32 m0, s48, 0x400
	s_nop 0
	global_load_lds_dwordx4 v251, s[12:13]
	s_cmp_lt_u32 s33, 29
	s_cselect_b32 s43, 0x10000, 0
	s_add_u32 s8, s8, s43
	s_addc_u32 s9, s9, 0
	s_cmp_lt_u32 s33, 29
	s_cselect_b32 s43, 0x2000, 0
	s_add_u32 s10, s10, s43
	s_addc_u32 s11, s11, 0
	s_cmp_lt_u32 s33, 29
	s_cselect_b32 s43, 0x4000, 0
	s_add_u32 s12, s12, s43
	s_addc_u32 s13, s13, 0
	s_waitcnt lgkmcnt(6)
	v_mfma_f32_16x16x32_bf16 v[60:63], v[12:15], v[44:47], v[60:63]
	v_mfma_f32_16x16x32_bf16 v[64:67], v[12:15], v[48:51], v[64:67]
	v_mfma_f32_16x16x32_bf16 v[68:71], v[16:19], v[44:47], v[68:71]
	v_mfma_f32_16x16x32_bf16 v[72:75], v[16:19], v[48:51], v[72:75]
	v_mfma_f32_16x16x32_bf16 v[76:79], v[20:23], v[44:47], v[76:79]
	v_mfma_f32_16x16x32_bf16 v[80:83], v[20:23], v[48:51], v[80:83]
	v_mfma_f32_16x16x32_bf16 v[84:87], v[24:27], v[44:47], v[84:87]
	v_mfma_f32_16x16x32_bf16 v[88:91], v[24:27], v[48:51], v[88:91]
	s_waitcnt lgkmcnt(0)
	v_mfma_f32_16x16x32_bf16 v[60:63], v[28:31], v[52:55], v[60:63]
	v_mfma_f32_16x16x32_bf16 v[64:67], v[28:31], v[56:59], v[64:67]
	v_mfma_f32_16x16x32_bf16 v[68:71], v[32:35], v[52:55], v[68:71]
	v_mfma_f32_16x16x32_bf16 v[72:75], v[32:35], v[56:59], v[72:75]
	v_mfma_f32_16x16x32_bf16 v[76:79], v[36:39], v[52:55], v[76:79]
	v_mfma_f32_16x16x32_bf16 v[80:83], v[36:39], v[56:59], v[80:83]
	v_mfma_f32_16x16x32_bf16 v[84:87], v[40:43], v[52:55], v[84:87]
	v_mfma_f32_16x16x32_bf16 v[88:91], v[40:43], v[56:59], v[88:91]
	s_nop 3
	global_load_dwordx4 v[108:111], v249, s[16:17]
	s_cmp_lt_u32 s33, 28
	s_cselect_b32 s43, 0x200, 0
	s_add_u32 s16, s16, s43
	s_addc_u32 s17, s17, 0
	s_add_i32 s33, s33, 1
	s_nop 7
	s_nop 7
	v_cvt_pk_bf16_f32 v140, v60, v61
	v_cvt_pk_bf16_f32 v141, v62, v63
	ds_write_b64 v215, v[140:141] offset:0
	v_cvt_pk_bf16_f32 v144, v64, v65
	v_cvt_pk_bf16_f32 v145, v66, v67
	ds_write_b64 v215, v[144:145] offset:4096
	s_nop 1
	v_cvt_pk_bf16_f32 v140, v68, v69
	v_cvt_pk_bf16_f32 v141, v70, v71
	ds_write_b64 v214, v[140:141] offset:0
	v_cvt_pk_bf16_f32 v144, v72, v73
	v_cvt_pk_bf16_f32 v145, v74, v75
	ds_write_b64 v214, v[144:145] offset:4096
	s_nop 1
	v_cvt_pk_bf16_f32 v140, v76, v77
	v_cvt_pk_bf16_f32 v141, v78, v79
	ds_write_b64 v213, v[140:141] offset:0
	v_cvt_pk_bf16_f32 v144, v80, v81
	v_cvt_pk_bf16_f32 v145, v82, v83
	ds_write_b64 v213, v[144:145] offset:4096
	s_nop 1
	v_cvt_pk_bf16_f32 v140, v84, v85
	v_cvt_pk_bf16_f32 v141, v86, v87
	ds_write_b64 v212, v[140:141] offset:0
	v_cvt_pk_bf16_f32 v144, v88, v89
	v_cvt_pk_bf16_f32 v145, v90, v91
	ds_write_b64 v212, v[144:145] offset:4096
	s_nop 1
	s_waitcnt vmcnt(7)
	s_waitcnt lgkmcnt(0)
	s_barrier
	ds_read_b128 v[44:47], v217 offset:0
	ds_read_b128 v[48:51], v217 offset:2048
	ds_read_b128 v[12:15], v225 offset:0
	ds_read_b128 v[16:19], v225 offset:2048
	ds_read_b128 v[20:23], v225 offset:4096
	ds_read_b128 v[24:27], v225 offset:6144
	ds_read_b128 v[52:55], v216 offset:0
	ds_read_b128 v[56:59], v216 offset:2048
	ds_read_b128 v[28:31], v224 offset:0
	ds_read_b128 v[32:35], v224 offset:2048
	ds_read_b128 v[36:39], v224 offset:4096
	ds_read_b128 v[40:43], v224 offset:6144
	s_waitcnt vmcnt(12)
	v_mov_b32_dpp v96, v124 quad_perm:[0,0,0,0] row_mask:0xf bank_mask:0xf
	v_mov_b32_dpp v97, v125 quad_perm:[0,0,0,0] row_mask:0xf bank_mask:0xf
	v_mov_b32_dpp v98, v126 quad_perm:[0,0,0,0] row_mask:0xf bank_mask:0xf
	v_mov_b32_dpp v99, v127 quad_perm:[0,0,0,0] row_mask:0xf bank_mask:0xf
	v_mov_b32_dpp v100, v124 quad_perm:[1,1,1,1] row_mask:0xf bank_mask:0xf
	v_mov_b32_dpp v101, v125 quad_perm:[1,1,1,1] row_mask:0xf bank_mask:0xf
	v_mov_b32_dpp v102, v126 quad_perm:[1,1,1,1] row_mask:0xf bank_mask:0xf
	v_mov_b32_dpp v103, v127 quad_perm:[1,1,1,1] row_mask:0xf bank_mask:0xf
	v_mov_b32_dpp v104, v124 quad_perm:[2,2,2,2] row_mask:0xf bank_mask:0xf
	v_mov_b32_dpp v105, v125 quad_perm:[2,2,2,2] row_mask:0xf bank_mask:0xf
	v_mov_b32_dpp v106, v126 quad_perm:[2,2,2,2] row_mask:0xf bank_mask:0xf
	v_mov_b32_dpp v107, v127 quad_perm:[2,2,2,2] row_mask:0xf bank_mask:0xf
	v_mov_b32_dpp v112, v124 quad_perm:[3,3,3,3] row_mask:0xf bank_mask:0xf
	v_mov_b32_dpp v113, v125 quad_perm:[3,3,3,3] row_mask:0xf bank_mask:0xf
	v_mov_b32_dpp v114, v126 quad_perm:[3,3,3,3] row_mask:0xf bank_mask:0xf
	v_mov_b32_dpp v115, v127 quad_perm:[3,3,3,3] row_mask:0xf bank_mask:0xf
	v_pk_mul_f32 v[60:61], v[60:61], v[96:97]
	v_pk_mul_f32 v[62:63], v[62:63], v[98:99]
	v_pk_mul_f32 v[64:65], v[64:65], v[96:97]
	v_pk_mul_f32 v[66:67], v[66:67], v[98:99]
	v_pk_mul_f32 v[68:69], v[68:69], v[100:101]
	v_pk_mul_f32 v[70:71], v[70:71], v[102:103]
	v_pk_mul_f32 v[72:73], v[72:73], v[100:101]
	v_pk_mul_f32 v[74:75], v[74:75], v[102:103]
	v_pk_mul_f32 v[76:77], v[76:77], v[104:105]
	v_pk_mul_f32 v[78:79], v[78:79], v[106:107]
	v_pk_mul_f32 v[80:81], v[80:81], v[104:105]
	v_pk_mul_f32 v[82:83], v[82:83], v[106:107]
	v_pk_mul_f32 v[84:85], v[84:85], v[112:113]
	v_pk_mul_f32 v[86:87], v[86:87], v[114:115]
	v_pk_mul_f32 v[88:89], v[88:89], v[112:113]
	v_pk_mul_f32 v[90:91], v[90:91], v[114:115]
	s_add_i32 m0, s46, 0xa000
	s_nop 0
	global_load_lds_dwordx4 v255, s[8:9]
	s_add_i32 m0, s46, 0xa400
	s_nop 0
	global_load_lds_dwordx4 v254, s[8:9]
	s_add_i32 m0, s47, 0xa000
	s_nop 0
	global_load_lds_dwordx4 v253, s[10:11]
	s_add_i32 m0, s48, 0xa000
	s_nop 0
	global_load_lds_dwordx4 v252, s[12:13]
	s_add_i32 m0, s48, 0xa400
	s_nop 0
	global_load_lds_dwordx4 v251, s[12:13]
	s_cmp_lt_u32 s33, 29
	s_cselect_b32 s43, 0x10000, 0
	s_add_u32 s8, s8, s43
	s_addc_u32 s9, s9, 0
	s_cmp_lt_u32 s33, 29
	s_cselect_b32 s43, 0x2000, 0
	s_add_u32 s10, s10, s43
	s_addc_u32 s11, s11, 0
	s_cmp_lt_u32 s33, 29
	s_cselect_b32 s43, 0x4000, 0
	s_add_u32 s12, s12, s43
	s_addc_u32 s13, s13, 0
	s_waitcnt lgkmcnt(6)
	v_mfma_f32_16x16x32_bf16 v[60:63], v[12:15], v[44:47], v[60:63]
	v_mfma_f32_16x16x32_bf16 v[64:67], v[12:15], v[48:51], v[64:67]
	v_mfma_f32_16x16x32_bf16 v[68:71], v[16:19], v[44:47], v[68:71]
	v_mfma_f32_16x16x32_bf16 v[72:75], v[16:19], v[48:51], v[72:75]
	v_mfma_f32_16x16x32_bf16 v[76:79], v[20:23], v[44:47], v[76:79]
	v_mfma_f32_16x16x32_bf16 v[80:83], v[20:23], v[48:51], v[80:83]
	v_mfma_f32_16x16x32_bf16 v[84:87], v[24:27], v[44:47], v[84:87]
	v_mfma_f32_16x16x32_bf16 v[88:91], v[24:27], v[48:51], v[88:91]
	s_waitcnt lgkmcnt(0)
	v_mfma_f32_16x16x32_bf16 v[60:63], v[28:31], v[52:55], v[60:63]
	v_mfma_f32_16x16x32_bf16 v[64:67], v[28:31], v[56:59], v[64:67]
	v_mfma_f32_16x16x32_bf16 v[68:71], v[32:35], v[52:55], v[68:71]
	v_mfma_f32_16x16x32_bf16 v[72:75], v[32:35], v[56:59], v[72:75]
	v_mfma_f32_16x16x32_bf16 v[76:79], v[36:39], v[52:55], v[76:79]
	v_mfma_f32_16x16x32_bf16 v[80:83], v[36:39], v[56:59], v[80:83]
	v_mfma_f32_16x16x32_bf16 v[84:87], v[40:43], v[52:55], v[84:87]
	v_mfma_f32_16x16x32_bf16 v[88:91], v[40:43], v[56:59], v[88:91]
	s_nop 3
	global_load_dwordx4 v[124:127], v249, s[16:17]
	s_cmp_lt_u32 s33, 28
	s_cselect_b32 s43, 0x200, 0
	s_add_u32 s16, s16, s43
	s_addc_u32 s17, s17, 0
	s_add_i32 s33, s33, 1
	s_nop 7
	s_nop 7
	v_cvt_pk_bf16_f32 v140, v60, v61
	v_cvt_pk_bf16_f32 v141, v62, v63
	ds_write_b64 v215, v[140:141] offset:12544
	v_cvt_pk_bf16_f32 v144, v64, v65
	v_cvt_pk_bf16_f32 v145, v66, v67
	ds_write_b64 v215, v[144:145] offset:16640
	s_nop 1
	v_cvt_pk_bf16_f32 v140, v68, v69
	v_cvt_pk_bf16_f32 v141, v70, v71
	ds_write_b64 v214, v[140:141] offset:12544
	v_cvt_pk_bf16_f32 v144, v72, v73
	v_cvt_pk_bf16_f32 v145, v74, v75
	ds_write_b64 v214, v[144:145] offset:16640
	s_nop 1
	v_cvt_pk_bf16_f32 v140, v76, v77
	v_cvt_pk_bf16_f32 v141, v78, v79
	ds_write_b64 v213, v[140:141] offset:12544
	v_cvt_pk_bf16_f32 v144, v80, v81
	v_cvt_pk_bf16_f32 v145, v82, v83
	ds_write_b64 v213, v[144:145] offset:16640
	s_nop 1
	v_cvt_pk_bf16_f32 v140, v84, v85
	v_cvt_pk_bf16_f32 v141, v86, v87
	ds_write_b64 v212, v[140:141] offset:12544
	v_cvt_pk_bf16_f32 v144, v88, v89
	v_cvt_pk_bf16_f32 v145, v90, v91
	ds_write_b64 v212, v[144:145] offset:16640
	s_nop 1
	s_waitcnt vmcnt(7)
	s_waitcnt lgkmcnt(0)
	s_barrier
	ds_read_b128 v[44:47], v217 offset:12288
	ds_read_b128 v[48:51], v217 offset:14336
	ds_read_b128 v[12:15], v227 offset:0
	ds_read_b128 v[16:19], v227 offset:2048
	ds_read_b128 v[20:23], v227 offset:4096
	ds_read_b128 v[24:27], v227 offset:6144
	ds_read_b128 v[52:55], v216 offset:12288
	ds_read_b128 v[56:59], v216 offset:14336
	ds_read_b128 v[28:31], v226 offset:0
	ds_read_b128 v[32:35], v226 offset:2048
	ds_read_b128 v[36:39], v226 offset:4096
	ds_read_b128 v[40:43], v226 offset:6144
	s_waitcnt vmcnt(12)
	v_mov_b32_dpp v96, v92 quad_perm:[0,0,0,0] row_mask:0xf bank_mask:0xf
	v_mov_b32_dpp v97, v93 quad_perm:[0,0,0,0] row_mask:0xf bank_mask:0xf
	v_mov_b32_dpp v98, v94 quad_perm:[0,0,0,0] row_mask:0xf bank_mask:0xf
	v_mov_b32_dpp v99, v95 quad_perm:[0,0,0,0] row_mask:0xf bank_mask:0xf
	v_mov_b32_dpp v100, v92 quad_perm:[1,1,1,1] row_mask:0xf bank_mask:0xf
	v_mov_b32_dpp v101, v93 quad_perm:[1,1,1,1] row_mask:0xf bank_mask:0xf
	v_mov_b32_dpp v102, v94 quad_perm:[1,1,1,1] row_mask:0xf bank_mask:0xf
	v_mov_b32_dpp v103, v95 quad_perm:[1,1,1,1] row_mask:0xf bank_mask:0xf
	v_mov_b32_dpp v104, v92 quad_perm:[2,2,2,2] row_mask:0xf bank_mask:0xf
	v_mov_b32_dpp v105, v93 quad_perm:[2,2,2,2] row_mask:0xf bank_mask:0xf
	v_mov_b32_dpp v106, v94 quad_perm:[2,2,2,2] row_mask:0xf bank_mask:0xf
	v_mov_b32_dpp v107, v95 quad_perm:[2,2,2,2] row_mask:0xf bank_mask:0xf
	v_mov_b32_dpp v112, v92 quad_perm:[3,3,3,3] row_mask:0xf bank_mask:0xf
	v_mov_b32_dpp v113, v93 quad_perm:[3,3,3,3] row_mask:0xf bank_mask:0xf
	v_mov_b32_dpp v114, v94 quad_perm:[3,3,3,3] row_mask:0xf bank_mask:0xf
	v_mov_b32_dpp v115, v95 quad_perm:[3,3,3,3] row_mask:0xf bank_mask:0xf
	v_pk_mul_f32 v[60:61], v[60:61], v[96:97]
	v_pk_mul_f32 v[62:63], v[62:63], v[98:99]
	v_pk_mul_f32 v[64:65], v[64:65], v[96:97]
	v_pk_mul_f32 v[66:67], v[66:67], v[98:99]
	v_pk_mul_f32 v[68:69], v[68:69], v[100:101]
	v_pk_mul_f32 v[70:71], v[70:71], v[102:103]
	v_pk_mul_f32 v[72:73], v[72:73], v[100:101]
	v_pk_mul_f32 v[74:75], v[74:75], v[102:103]
	v_pk_mul_f32 v[76:77], v[76:77], v[104:105]
	v_pk_mul_f32 v[78:79], v[78:79], v[106:107]
	v_pk_mul_f32 v[80:81], v[80:81], v[104:105]
	v_pk_mul_f32 v[82:83], v[82:83], v[106:107]
	v_pk_mul_f32 v[84:85], v[84:85], v[112:113]
	v_pk_mul_f32 v[86:87], v[86:87], v[114:115]
	v_pk_mul_f32 v[88:89], v[88:89], v[112:113]
	v_pk_mul_f32 v[90:91], v[90:91], v[114:115]
	s_add_i32 m0, s46, 0x14000
	s_nop 0
	global_load_lds_dwordx4 v255, s[8:9]
	s_add_i32 m0, s46, 0x14400
	s_nop 0
	global_load_lds_dwordx4 v254, s[8:9]
	s_add_i32 m0, s47, 0x14000
	s_nop 0
	global_load_lds_dwordx4 v253, s[10:11]
	s_add_i32 m0, s48, 0x14000
	s_nop 0
	global_load_lds_dwordx4 v252, s[12:13]
	s_add_i32 m0, s48, 0x14400
	s_nop 0
	global_load_lds_dwordx4 v251, s[12:13]
	s_cmp_lt_u32 s33, 29
	s_cselect_b32 s43, 0x10000, 0
	s_add_u32 s8, s8, s43
	s_addc_u32 s9, s9, 0
	s_cmp_lt_u32 s33, 29
	s_cselect_b32 s43, 0x2000, 0
	s_add_u32 s10, s10, s43
	s_addc_u32 s11, s11, 0
	s_cmp_lt_u32 s33, 29
	s_cselect_b32 s43, 0x4000, 0
	s_add_u32 s12, s12, s43
	s_addc_u32 s13, s13, 0
	s_waitcnt lgkmcnt(6)
	v_mfma_f32_16x16x32_bf16 v[60:63], v[12:15], v[44:47], v[60:63]
	v_mfma_f32_16x16x32_bf16 v[64:67], v[12:15], v[48:51], v[64:67]
	v_mfma_f32_16x16x32_bf16 v[68:71], v[16:19], v[44:47], v[68:71]
	v_mfma_f32_16x16x32_bf16 v[72:75], v[16:19], v[48:51], v[72:75]
	v_mfma_f32_16x16x32_bf16 v[76:79], v[20:23], v[44:47], v[76:79]
	v_mfma_f32_16x16x32_bf16 v[80:83], v[20:23], v[48:51], v[80:83]
	v_mfma_f32_16x16x32_bf16 v[84:87], v[24:27], v[44:47], v[84:87]
	v_mfma_f32_16x16x32_bf16 v[88:91], v[24:27], v[48:51], v[88:91]
	s_waitcnt lgkmcnt(0)
	v_mfma_f32_16x16x32_bf16 v[60:63], v[28:31], v[52:55], v[60:63]
	v_mfma_f32_16x16x32_bf16 v[64:67], v[28:31], v[56:59], v[64:67]
	v_mfma_f32_16x16x32_bf16 v[68:71], v[32:35], v[52:55], v[68:71]
	v_mfma_f32_16x16x32_bf16 v[72:75], v[32:35], v[56:59], v[72:75]
	v_mfma_f32_16x16x32_bf16 v[76:79], v[36:39], v[52:55], v[76:79]
	v_mfma_f32_16x16x32_bf16 v[80:83], v[36:39], v[56:59], v[80:83]
	v_mfma_f32_16x16x32_bf16 v[84:87], v[40:43], v[52:55], v[84:87]
	v_mfma_f32_16x16x32_bf16 v[88:91], v[40:43], v[56:59], v[88:91]
	s_nop 3
	global_load_dwordx4 v[92:95], v249, s[16:17]
	s_cmp_lt_u32 s33, 28
	s_cselect_b32 s43, 0x200, 0
	s_add_u32 s16, s16, s43
	s_addc_u32 s17, s17, 0
	s_add_i32 s33, s33, 1
	s_nop 7
	s_nop 7
	v_cvt_pk_bf16_f32 v140, v60, v61
	v_cvt_pk_bf16_f32 v141, v62, v63
	ds_write_b64 v215, v[140:141] offset:0
	v_cvt_pk_bf16_f32 v144, v64, v65
	v_cvt_pk_bf16_f32 v145, v66, v67
	ds_write_b64 v215, v[144:145] offset:4096
	s_nop 1
	v_cvt_pk_bf16_f32 v140, v68, v69
	v_cvt_pk_bf16_f32 v141, v70, v71
	ds_write_b64 v214, v[140:141] offset:0
	v_cvt_pk_bf16_f32 v144, v72, v73
	v_cvt_pk_bf16_f32 v145, v74, v75
	ds_write_b64 v214, v[144:145] offset:4096
	s_nop 1
	v_cvt_pk_bf16_f32 v140, v76, v77
	v_cvt_pk_bf16_f32 v141, v78, v79
	ds_write_b64 v213, v[140:141] offset:0
	v_cvt_pk_bf16_f32 v144, v80, v81
	v_cvt_pk_bf16_f32 v145, v82, v83
	ds_write_b64 v213, v[144:145] offset:4096
	s_nop 1
	v_cvt_pk_bf16_f32 v140, v84, v85
	v_cvt_pk_bf16_f32 v141, v86, v87
	ds_write_b64 v212, v[140:141] offset:0
	v_cvt_pk_bf16_f32 v144, v88, v89
	v_cvt_pk_bf16_f32 v145, v90, v91
	ds_write_b64 v212, v[144:145] offset:4096
	s_nop 1
	s_waitcnt vmcnt(7)
	s_waitcnt lgkmcnt(0)
	s_barrier
	ds_read_b128 v[44:47], v217 offset:0
	ds_read_b128 v[48:51], v217 offset:2048
	ds_read_b128 v[12:15], v227 offset:40960
	ds_read_b128 v[16:19], v227 offset:43008
	ds_read_b128 v[20:23], v227 offset:45056
	ds_read_b128 v[24:27], v227 offset:47104
	ds_read_b128 v[52:55], v216 offset:0
	ds_read_b128 v[56:59], v216 offset:2048
	ds_read_b128 v[28:31], v226 offset:40960
	ds_read_b128 v[32:35], v226 offset:43008
	ds_read_b128 v[36:39], v226 offset:45056
	ds_read_b128 v[40:43], v226 offset:47104
	s_waitcnt vmcnt(12)
	v_mov_b32_dpp v96, v108 quad_perm:[0,0,0,0] row_mask:0xf bank_mask:0xf
	v_mov_b32_dpp v97, v109 quad_perm:[0,0,0,0] row_mask:0xf bank_mask:0xf
	v_mov_b32_dpp v98, v110 quad_perm:[0,0,0,0] row_mask:0xf bank_mask:0xf
	v_mov_b32_dpp v99, v111 quad_perm:[0,0,0,0] row_mask:0xf bank_mask:0xf
	v_mov_b32_dpp v100, v108 quad_perm:[1,1,1,1] row_mask:0xf bank_mask:0xf
	v_mov_b32_dpp v101, v109 quad_perm:[1,1,1,1] row_mask:0xf bank_mask:0xf
	v_mov_b32_dpp v102, v110 quad_perm:[1,1,1,1] row_mask:0xf bank_mask:0xf
	v_mov_b32_dpp v103, v111 quad_perm:[1,1,1,1] row_mask:0xf bank_mask:0xf
	v_mov_b32_dpp v104, v108 quad_perm:[2,2,2,2] row_mask:0xf bank_mask:0xf
	v_mov_b32_dpp v105, v109 quad_perm:[2,2,2,2] row_mask:0xf bank_mask:0xf
	v_mov_b32_dpp v106, v110 quad_perm:[2,2,2,2] row_mask:0xf bank_mask:0xf
	v_mov_b32_dpp v107, v111 quad_perm:[2,2,2,2] row_mask:0xf bank_mask:0xf
	v_mov_b32_dpp v112, v108 quad_perm:[3,3,3,3] row_mask:0xf bank_mask:0xf
	v_mov_b32_dpp v113, v109 quad_perm:[3,3,3,3] row_mask:0xf bank_mask:0xf
	v_mov_b32_dpp v114, v110 quad_perm:[3,3,3,3] row_mask:0xf bank_mask:0xf
	v_mov_b32_dpp v115, v111 quad_perm:[3,3,3,3] row_mask:0xf bank_mask:0xf
	v_pk_mul_f32 v[60:61], v[60:61], v[96:97]
	v_pk_mul_f32 v[62:63], v[62:63], v[98:99]
	v_pk_mul_f32 v[64:65], v[64:65], v[96:97]
	v_pk_mul_f32 v[66:67], v[66:67], v[98:99]
	v_pk_mul_f32 v[68:69], v[68:69], v[100:101]
	v_pk_mul_f32 v[70:71], v[70:71], v[102:103]
	v_pk_mul_f32 v[72:73], v[72:73], v[100:101]
	v_pk_mul_f32 v[74:75], v[74:75], v[102:103]
	v_pk_mul_f32 v[76:77], v[76:77], v[104:105]
	v_pk_mul_f32 v[78:79], v[78:79], v[106:107]
	v_pk_mul_f32 v[80:81], v[80:81], v[104:105]
	v_pk_mul_f32 v[82:83], v[82:83], v[106:107]
	v_pk_mul_f32 v[84:85], v[84:85], v[112:113]
	v_pk_mul_f32 v[86:87], v[86:87], v[114:115]
	v_pk_mul_f32 v[88:89], v[88:89], v[112:113]
	v_pk_mul_f32 v[90:91], v[90:91], v[114:115]
	s_mov_b32 m0, s46
	s_nop 0
	global_load_lds_dwordx4 v255, s[8:9]
	s_add_i32 m0, s46, 0x400
	s_nop 0
	global_load_lds_dwordx4 v254, s[8:9]
	s_mov_b32 m0, s47
	s_nop 0
	global_load_lds_dwordx4 v253, s[10:11]
	s_mov_b32 m0, s48
	s_nop 0
	global_load_lds_dwordx4 v252, s[12:13]
	s_add_i32 m0, s48, 0x400
	s_nop 0
	global_load_lds_dwordx4 v251, s[12:13]
	s_cmp_lt_u32 s33, 29
	s_cselect_b32 s43, 0x10000, 0
	s_add_u32 s8, s8, s43
	s_addc_u32 s9, s9, 0
	s_cmp_lt_u32 s33, 29
	s_cselect_b32 s43, 0x2000, 0
	s_add_u32 s10, s10, s43
	s_addc_u32 s11, s11, 0
	s_cmp_lt_u32 s33, 29
	s_cselect_b32 s43, 0x4000, 0
	s_add_u32 s12, s12, s43
	s_addc_u32 s13, s13, 0
	s_waitcnt lgkmcnt(6)
	v_mfma_f32_16x16x32_bf16 v[60:63], v[12:15], v[44:47], v[60:63]
	v_mfma_f32_16x16x32_bf16 v[64:67], v[12:15], v[48:51], v[64:67]
	v_mfma_f32_16x16x32_bf16 v[68:71], v[16:19], v[44:47], v[68:71]
	v_mfma_f32_16x16x32_bf16 v[72:75], v[16:19], v[48:51], v[72:75]
	v_mfma_f32_16x16x32_bf16 v[76:79], v[20:23], v[44:47], v[76:79]
	v_mfma_f32_16x16x32_bf16 v[80:83], v[20:23], v[48:51], v[80:83]
	v_mfma_f32_16x16x32_bf16 v[84:87], v[24:27], v[44:47], v[84:87]
	v_mfma_f32_16x16x32_bf16 v[88:91], v[24:27], v[48:51], v[88:91]
	s_waitcnt lgkmcnt(0)
	v_mfma_f32_16x16x32_bf16 v[60:63], v[28:31], v[52:55], v[60:63]
	v_mfma_f32_16x16x32_bf16 v[64:67], v[28:31], v[56:59], v[64:67]
	v_mfma_f32_16x16x32_bf16 v[68:71], v[32:35], v[52:55], v[68:71]
	v_mfma_f32_16x16x32_bf16 v[72:75], v[32:35], v[56:59], v[72:75]
	v_mfma_f32_16x16x32_bf16 v[76:79], v[36:39], v[52:55], v[76:79]
	v_mfma_f32_16x16x32_bf16 v[80:83], v[36:39], v[56:59], v[80:83]
	v_mfma_f32_16x16x32_bf16 v[84:87], v[40:43], v[52:55], v[84:87]
	v_mfma_f32_16x16x32_bf16 v[88:91], v[40:43], v[56:59], v[88:91]
	s_nop 3
	global_load_dwordx4 v[108:111], v249, s[16:17]
	s_cmp_lt_u32 s33, 28
	s_cselect_b32 s43, 0x200, 0
	s_add_u32 s16, s16, s43
	s_addc_u32 s17, s17, 0
	s_add_i32 s33, s33, 1
	s_nop 7
	s_nop 7
	v_cvt_pk_bf16_f32 v140, v60, v61
	v_cvt_pk_bf16_f32 v141, v62, v63
	ds_write_b64 v215, v[140:141] offset:12544
	v_cvt_pk_bf16_f32 v144, v64, v65
	v_cvt_pk_bf16_f32 v145, v66, v67
	ds_write_b64 v215, v[144:145] offset:16640
	s_nop 1
	v_cvt_pk_bf16_f32 v140, v68, v69
	v_cvt_pk_bf16_f32 v141, v70, v71
	ds_write_b64 v214, v[140:141] offset:12544
	v_cvt_pk_bf16_f32 v144, v72, v73
	v_cvt_pk_bf16_f32 v145, v74, v75
	ds_write_b64 v214, v[144:145] offset:16640
	s_nop 1
	v_cvt_pk_bf16_f32 v140, v76, v77
	v_cvt_pk_bf16_f32 v141, v78, v79
	ds_write_b64 v213, v[140:141] offset:12544
	v_cvt_pk_bf16_f32 v144, v80, v81
	v_cvt_pk_bf16_f32 v145, v82, v83
	ds_write_b64 v213, v[144:145] offset:16640
	s_nop 1
	v_cvt_pk_bf16_f32 v140, v84, v85
	v_cvt_pk_bf16_f32 v141, v86, v87
	ds_write_b64 v212, v[140:141] offset:12544
	v_cvt_pk_bf16_f32 v144, v88, v89
	v_cvt_pk_bf16_f32 v145, v90, v91
	ds_write_b64 v212, v[144:145] offset:16640
	s_nop 1
	s_waitcnt vmcnt(7)
	s_waitcnt lgkmcnt(0)
	s_barrier
	ds_read_b128 v[44:47], v217 offset:12288
	ds_read_b128 v[48:51], v217 offset:14336
	ds_read_b128 v[12:15], v225 offset:0
	ds_read_b128 v[16:19], v225 offset:2048
	ds_read_b128 v[20:23], v225 offset:4096
	ds_read_b128 v[24:27], v225 offset:6144
	ds_read_b128 v[52:55], v216 offset:12288
	ds_read_b128 v[56:59], v216 offset:14336
	ds_read_b128 v[28:31], v224 offset:0
	ds_read_b128 v[32:35], v224 offset:2048
	ds_read_b128 v[36:39], v224 offset:4096
	ds_read_b128 v[40:43], v224 offset:6144
	s_waitcnt vmcnt(12)
	v_mov_b32_dpp v96, v124 quad_perm:[0,0,0,0] row_mask:0xf bank_mask:0xf
	v_mov_b32_dpp v97, v125 quad_perm:[0,0,0,0] row_mask:0xf bank_mask:0xf
	v_mov_b32_dpp v98, v126 quad_perm:[0,0,0,0] row_mask:0xf bank_mask:0xf
	v_mov_b32_dpp v99, v127 quad_perm:[0,0,0,0] row_mask:0xf bank_mask:0xf
	v_mov_b32_dpp v100, v124 quad_perm:[1,1,1,1] row_mask:0xf bank_mask:0xf
	v_mov_b32_dpp v101, v125 quad_perm:[1,1,1,1] row_mask:0xf bank_mask:0xf
	v_mov_b32_dpp v102, v126 quad_perm:[1,1,1,1] row_mask:0xf bank_mask:0xf
	v_mov_b32_dpp v103, v127 quad_perm:[1,1,1,1] row_mask:0xf bank_mask:0xf
	v_mov_b32_dpp v104, v124 quad_perm:[2,2,2,2] row_mask:0xf bank_mask:0xf
	v_mov_b32_dpp v105, v125 quad_perm:[2,2,2,2] row_mask:0xf bank_mask:0xf
	v_mov_b32_dpp v106, v126 quad_perm:[2,2,2,2] row_mask:0xf bank_mask:0xf
	v_mov_b32_dpp v107, v127 quad_perm:[2,2,2,2] row_mask:0xf bank_mask:0xf
	v_mov_b32_dpp v112, v124 quad_perm:[3,3,3,3] row_mask:0xf bank_mask:0xf
	v_mov_b32_dpp v113, v125 quad_perm:[3,3,3,3] row_mask:0xf bank_mask:0xf
	v_mov_b32_dpp v114, v126 quad_perm:[3,3,3,3] row_mask:0xf bank_mask:0xf
	v_mov_b32_dpp v115, v127 quad_perm:[3,3,3,3] row_mask:0xf bank_mask:0xf
	v_pk_mul_f32 v[60:61], v[60:61], v[96:97]
	v_pk_mul_f32 v[62:63], v[62:63], v[98:99]
	v_pk_mul_f32 v[64:65], v[64:65], v[96:97]
	v_pk_mul_f32 v[66:67], v[66:67], v[98:99]
	v_pk_mul_f32 v[68:69], v[68:69], v[100:101]
	v_pk_mul_f32 v[70:71], v[70:71], v[102:103]
	v_pk_mul_f32 v[72:73], v[72:73], v[100:101]
	v_pk_mul_f32 v[74:75], v[74:75], v[102:103]
	v_pk_mul_f32 v[76:77], v[76:77], v[104:105]
	v_pk_mul_f32 v[78:79], v[78:79], v[106:107]
	v_pk_mul_f32 v[80:81], v[80:81], v[104:105]
	v_pk_mul_f32 v[82:83], v[82:83], v[106:107]
	v_pk_mul_f32 v[84:85], v[84:85], v[112:113]
	v_pk_mul_f32 v[86:87], v[86:87], v[114:115]
	v_pk_mul_f32 v[88:89], v[88:89], v[112:113]
	v_pk_mul_f32 v[90:91], v[90:91], v[114:115]
	s_add_i32 m0, s46, 0xa000
	s_nop 0
	global_load_lds_dwordx4 v255, s[8:9]
	s_add_i32 m0, s46, 0xa400
	s_nop 0
	global_load_lds_dwordx4 v254, s[8:9]
	s_add_i32 m0, s47, 0xa000
	s_nop 0
	global_load_lds_dwordx4 v253, s[10:11]
	s_add_i32 m0, s48, 0xa000
	s_nop 0
	global_load_lds_dwordx4 v252, s[12:13]
	s_add_i32 m0, s48, 0xa400
	s_nop 0
	global_load_lds_dwordx4 v251, s[12:13]
	s_cmp_lt_u32 s33, 29
	s_cselect_b32 s43, 0x10000, 0
	s_add_u32 s8, s8, s43
	s_addc_u32 s9, s9, 0
	s_cmp_lt_u32 s33, 29
	s_cselect_b32 s43, 0x2000, 0
	s_add_u32 s10, s10, s43
	s_addc_u32 s11, s11, 0
	s_cmp_lt_u32 s33, 29
	s_cselect_b32 s43, 0x4000, 0
	s_add_u32 s12, s12, s43
	s_addc_u32 s13, s13, 0
	s_waitcnt lgkmcnt(6)
	v_mfma_f32_16x16x32_bf16 v[60:63], v[12:15], v[44:47], v[60:63]
	v_mfma_f32_16x16x32_bf16 v[64:67], v[12:15], v[48:51], v[64:67]
	v_mfma_f32_16x16x32_bf16 v[68:71], v[16:19], v[44:47], v[68:71]
	v_mfma_f32_16x16x32_bf16 v[72:75], v[16:19], v[48:51], v[72:75]
	v_mfma_f32_16x16x32_bf16 v[76:79], v[20:23], v[44:47], v[76:79]
	v_mfma_f32_16x16x32_bf16 v[80:83], v[20:23], v[48:51], v[80:83]
	v_mfma_f32_16x16x32_bf16 v[84:87], v[24:27], v[44:47], v[84:87]
	v_mfma_f32_16x16x32_bf16 v[88:91], v[24:27], v[48:51], v[88:91]
	s_waitcnt lgkmcnt(0)
	v_mfma_f32_16x16x32_bf16 v[60:63], v[28:31], v[52:55], v[60:63]
	v_mfma_f32_16x16x32_bf16 v[64:67], v[28:31], v[56:59], v[64:67]
	v_mfma_f32_16x16x32_bf16 v[68:71], v[32:35], v[52:55], v[68:71]
	v_mfma_f32_16x16x32_bf16 v[72:75], v[32:35], v[56:59], v[72:75]
	v_mfma_f32_16x16x32_bf16 v[76:79], v[36:39], v[52:55], v[76:79]
	v_mfma_f32_16x16x32_bf16 v[80:83], v[36:39], v[56:59], v[80:83]
	v_mfma_f32_16x16x32_bf16 v[84:87], v[40:43], v[52:55], v[84:87]
	v_mfma_f32_16x16x32_bf16 v[88:91], v[40:43], v[56:59], v[88:91]
	s_nop 3
	global_load_dwordx4 v[124:127], v249, s[16:17]
	s_cmp_lt_u32 s33, 28
	s_cselect_b32 s43, 0x200, 0
	s_add_u32 s16, s16, s43
	s_addc_u32 s17, s17, 0
	s_add_i32 s33, s33, 1
	s_nop 7
	s_nop 7
	v_cvt_pk_bf16_f32 v140, v60, v61
	v_cvt_pk_bf16_f32 v141, v62, v63
	ds_write_b64 v215, v[140:141] offset:0
	v_cvt_pk_bf16_f32 v144, v64, v65
	v_cvt_pk_bf16_f32 v145, v66, v67
	ds_write_b64 v215, v[144:145] offset:4096
	s_nop 1
	v_cvt_pk_bf16_f32 v140, v68, v69
	v_cvt_pk_bf16_f32 v141, v70, v71
	ds_write_b64 v214, v[140:141] offset:0
	v_cvt_pk_bf16_f32 v144, v72, v73
	v_cvt_pk_bf16_f32 v145, v74, v75
	ds_write_b64 v214, v[144:145] offset:4096
	s_nop 1
	v_cvt_pk_bf16_f32 v140, v76, v77
	v_cvt_pk_bf16_f32 v141, v78, v79
	ds_write_b64 v213, v[140:141] offset:0
	v_cvt_pk_bf16_f32 v144, v80, v81
	v_cvt_pk_bf16_f32 v145, v82, v83
	ds_write_b64 v213, v[144:145] offset:4096
	s_nop 1
	v_cvt_pk_bf16_f32 v140, v84, v85
	v_cvt_pk_bf16_f32 v141, v86, v87
	ds_write_b64 v212, v[140:141] offset:0
	v_cvt_pk_bf16_f32 v144, v88, v89
	v_cvt_pk_bf16_f32 v145, v90, v91
	ds_write_b64 v212, v[144:145] offset:4096
	s_nop 1
	s_waitcnt vmcnt(7)
	s_waitcnt lgkmcnt(0)
	s_barrier
	s_cmp_lt_u32 s33, 30
	s_cbranch_scc1 .Lp3S_loop
	ds_read_b128 v[44:47], v217 offset:0
	ds_read_b128 v[48:51], v217 offset:2048
	ds_read_b128 v[12:15], v227 offset:0
	ds_read_b128 v[16:19], v227 offset:2048
	ds_read_b128 v[20:23], v227 offset:4096
	ds_read_b128 v[24:27], v227 offset:6144
	ds_read_b128 v[52:55], v216 offset:0
	ds_read_b128 v[56:59], v216 offset:2048
	ds_read_b128 v[28:31], v226 offset:0
	ds_read_b128 v[32:35], v226 offset:2048
	ds_read_b128 v[36:39], v226 offset:4096
	ds_read_b128 v[40:43], v226 offset:6144
	s_waitcnt vmcnt(12)
	v_mov_b32_dpp v96, v92 quad_perm:[0,0,0,0] row_mask:0xf bank_mask:0xf
	v_mov_b32_dpp v97, v93 quad_perm:[0,0,0,0] row_mask:0xf bank_mask:0xf
	v_mov_b32_dpp v98, v94 quad_perm:[0,0,0,0] row_mask:0xf bank_mask:0xf
	v_mov_b32_dpp v99, v95 quad_perm:[0,0,0,0] row_mask:0xf bank_mask:0xf
	v_mov_b32_dpp v100, v92 quad_perm:[1,1,1,1] row_mask:0xf bank_mask:0xf
	v_mov_b32_dpp v101, v93 quad_perm:[1,1,1,1] row_mask:0xf bank_mask:0xf
	v_mov_b32_dpp v102, v94 quad_perm:[1,1,1,1] row_mask:0xf bank_mask:0xf
	v_mov_b32_dpp v103, v95 quad_perm:[1,1,1,1] row_mask:0xf bank_mask:0xf
	v_mov_b32_dpp v104, v92 quad_perm:[2,2,2,2] row_mask:0xf bank_mask:0xf
	v_mov_b32_dpp v105, v93 quad_perm:[2,2,2,2] row_mask:0xf bank_mask:0xf
	v_mov_b32_dpp v106, v94 quad_perm:[2,2,2,2] row_mask:0xf bank_mask:0xf
	v_mov_b32_dpp v107, v95 quad_perm:[2,2,2,2] row_mask:0xf bank_mask:0xf
	v_mov_b32_dpp v112, v92 quad_perm:[3,3,3,3] row_mask:0xf bank_mask:0xf
	v_mov_b32_dpp v113, v93 quad_perm:[3,3,3,3] row_mask:0xf bank_mask:0xf
	v_mov_b32_dpp v114, v94 quad_perm:[3,3,3,3] row_mask:0xf bank_mask:0xf
	v_mov_b32_dpp v115, v95 quad_perm:[3,3,3,3] row_mask:0xf bank_mask:0xf
	v_pk_mul_f32 v[60:61], v[60:61], v[96:97]
	v_pk_mul_f32 v[62:63], v[62:63], v[98:99]
	v_pk_mul_f32 v[64:65], v[64:65], v[96:97]
	v_pk_mul_f32 v[66:67], v[66:67], v[98:99]
	v_pk_mul_f32 v[68:69], v[68:69], v[100:101]
	v_pk_mul_f32 v[70:71], v[70:71], v[102:103]
	v_pk_mul_f32 v[72:73], v[72:73], v[100:101]
	v_pk_mul_f32 v[74:75], v[74:75], v[102:103]
	v_pk_mul_f32 v[76:77], v[76:77], v[104:105]
	v_pk_mul_f32 v[78:79], v[78:79], v[106:107]
	v_pk_mul_f32 v[80:81], v[80:81], v[104:105]
	v_pk_mul_f32 v[82:83], v[82:83], v[106:107]
	v_pk_mul_f32 v[84:85], v[84:85], v[112:113]
	v_pk_mul_f32 v[86:87], v[86:87], v[114:115]
	v_pk_mul_f32 v[88:89], v[88:89], v[112:113]
	v_pk_mul_f32 v[90:91], v[90:91], v[114:115]
	s_add_i32 m0, s46, 0x14000
	s_nop 0
	global_load_lds_dwordx4 v255, s[8:9]
	s_add_i32 m0, s46, 0x14400
	s_nop 0
	global_load_lds_dwordx4 v254, s[8:9]
	s_add_i32 m0, s47, 0x14000
	s_nop 0
	global_load_lds_dwordx4 v253, s[10:11]
	s_add_i32 m0, s48, 0x14000
	s_nop 0
	global_load_lds_dwordx4 v252, s[12:13]
	s_add_i32 m0, s48, 0x14400
	s_nop 0
	global_load_lds_dwordx4 v251, s[12:13]
	s_cmp_lt_u32 s33, 29
	s_cselect_b32 s43, 0x10000, 0
	s_add_u32 s8, s8, s43
	s_addc_u32 s9, s9, 0
	s_cmp_lt_u32 s33, 29
	s_cselect_b32 s43, 0x2000, 0
	s_add_u32 s10, s10, s43
	s_addc_u32 s11, s11, 0
	s_cmp_lt_u32 s33, 29
	s_cselect_b32 s43, 0x4000, 0
	s_add_u32 s12, s12, s43
	s_addc_u32 s13, s13, 0
	s_waitcnt lgkmcnt(6)
	v_mfma_f32_16x16x32_bf16 v[60:63], v[12:15], v[44:47], v[60:63]
	v_mfma_f32_16x16x32_bf16 v[64:67], v[12:15], v[48:51], v[64:67]
	v_mfma_f32_16x16x32_bf16 v[68:71], v[16:19], v[44:47], v[68:71]
	v_mfma_f32_16x16x32_bf16 v[72:75], v[16:19], v[48:51], v[72:75]
	v_mfma_f32_16x16x32_bf16 v[76:79], v[20:23], v[44:47], v[76:79]
	v_mfma_f32_16x16x32_bf16 v[80:83], v[20:23], v[48:51], v[80:83]
	v_mfma_f32_16x16x32_bf16 v[84:87], v[24:27], v[44:47], v[84:87]
	v_mfma_f32_16x16x32_bf16 v[88:91], v[24:27], v[48:51], v[88:91]
	s_waitcnt lgkmcnt(0)
	v_mfma_f32_16x16x32_bf16 v[60:63], v[28:31], v[52:55], v[60:63]
	v_mfma_f32_16x16x32_bf16 v[64:67], v[28:31], v[56:59], v[64:67]
	v_mfma_f32_16x16x32_bf16 v[68:71], v[32:35], v[52:55], v[68:71]
	v_mfma_f32_16x16x32_bf16 v[72:75], v[32:35], v[56:59], v[72:75]
	v_mfma_f32_16x16x32_bf16 v[76:79], v[36:39], v[52:55], v[76:79]
	v_mfma_f32_16x16x32_bf16 v[80:83], v[36:39], v[56:59], v[80:83]
	v_mfma_f32_16x16x32_bf16 v[84:87], v[40:43], v[52:55], v[84:87]
	v_mfma_f32_16x16x32_bf16 v[88:91], v[40:43], v[56:59], v[88:91]
	s_nop 3
	global_load_dwordx4 v[92:95], v249, s[16:17]
	s_cmp_lt_u32 s33, 28
	s_cselect_b32 s43, 0x200, 0
	s_add_u32 s16, s16, s43
	s_addc_u32 s17, s17, 0
	s_add_i32 s33, s33, 1
	s_nop 7
	s_nop 7
	v_cvt_pk_bf16_f32 v140, v60, v61
	v_cvt_pk_bf16_f32 v141, v62, v63
	ds_write_b64 v215, v[140:141] offset:12544
	v_cvt_pk_bf16_f32 v144, v64, v65
	v_cvt_pk_bf16_f32 v145, v66, v67
	ds_write_b64 v215, v[144:145] offset:16640
	s_nop 1
	v_cvt_pk_bf16_f32 v140, v68, v69
	v_cvt_pk_bf16_f32 v141, v70, v71
	ds_write_b64 v214, v[140:141] offset:12544
	v_cvt_pk_bf16_f32 v144, v72, v73
	v_cvt_pk_bf16_f32 v145, v74, v75
	ds_write_b64 v214, v[144:145] offset:16640
	s_nop 1
	v_cvt_pk_bf16_f32 v140, v76, v77
	v_cvt_pk_bf16_f32 v141, v78, v79
	ds_write_b64 v213, v[140:141] offset:12544
	v_cvt_pk_bf16_f32 v144, v80, v81
	v_cvt_pk_bf16_f32 v145, v82, v83
	ds_write_b64 v213, v[144:145] offset:16640
	s_nop 1
	v_cvt_pk_bf16_f32 v140, v84, v85
	v_cvt_pk_bf16_f32 v141, v86, v87
	ds_write_b64 v212, v[140:141] offset:12544
	v_cvt_pk_bf16_f32 v144, v88, v89
	v_cvt_pk_bf16_f32 v145, v90, v91
	ds_write_b64 v212, v[144:145] offset:16640
	s_nop 1
	s_waitcnt vmcnt(7)
	s_waitcnt lgkmcnt(0)
	s_barrier
	ds_read_b128 v[44:47], v217 offset:12288
	ds_read_b128 v[48:51], v217 offset:14336
	ds_read_b128 v[12:15], v227 offset:40960
	ds_read_b128 v[16:19], v227 offset:43008
	ds_read_b128 v[20:23], v227 offset:45056
	ds_read_b128 v[24:27], v227 offset:47104
	ds_read_b128 v[52:55], v216 offset:12288
	ds_read_b128 v[56:59], v216 offset:14336
	ds_read_b128 v[28:31], v226 offset:40960
	ds_read_b128 v[32:35], v226 offset:43008
	ds_read_b128 v[36:39], v226 offset:45056
	ds_read_b128 v[40:43], v226 offset:47104
	s_waitcnt vmcnt(12)
	v_mov_b32_dpp v96, v108 quad_perm:[0,0,0,0] row_mask:0xf bank_mask:0xf
	v_mov_b32_dpp v97, v109 quad_perm:[0,0,0,0] row_mask:0xf bank_mask:0xf
	v_mov_b32_dpp v98, v110 quad_perm:[0,0,0,0] row_mask:0xf bank_mask:0xf
	v_mov_b32_dpp v99, v111 quad_perm:[0,0,0,0] row_mask:0xf bank_mask:0xf
	v_mov_b32_dpp v100, v108 quad_perm:[1,1,1,1] row_mask:0xf bank_mask:0xf
	v_mov_b32_dpp v101, v109 quad_perm:[1,1,1,1] row_mask:0xf bank_mask:0xf
	v_mov_b32_dpp v102, v110 quad_perm:[1,1,1,1] row_mask:0xf bank_mask:0xf
	v_mov_b32_dpp v103, v111 quad_perm:[1,1,1,1] row_mask:0xf bank_mask:0xf
	v_mov_b32_dpp v104, v108 quad_perm:[2,2,2,2] row_mask:0xf bank_mask:0xf
	v_mov_b32_dpp v105, v109 quad_perm:[2,2,2,2] row_mask:0xf bank_mask:0xf
	v_mov_b32_dpp v106, v110 quad_perm:[2,2,2,2] row_mask:0xf bank_mask:0xf
	v_mov_b32_dpp v107, v111 quad_perm:[2,2,2,2] row_mask:0xf bank_mask:0xf
	v_mov_b32_dpp v112, v108 quad_perm:[3,3,3,3] row_mask:0xf bank_mask:0xf
	v_mov_b32_dpp v113, v109 quad_perm:[3,3,3,3] row_mask:0xf bank_mask:0xf
	v_mov_b32_dpp v114, v110 quad_perm:[3,3,3,3] row_mask:0xf bank_mask:0xf
	v_mov_b32_dpp v115, v111 quad_perm:[3,3,3,3] row_mask:0xf bank_mask:0xf
	v_pk_mul_f32 v[60:61], v[60:61], v[96:97]
	v_pk_mul_f32 v[62:63], v[62:63], v[98:99]
	v_pk_mul_f32 v[64:65], v[64:65], v[96:97]
	v_pk_mul_f32 v[66:67], v[66:67], v[98:99]
	v_pk_mul_f32 v[68:69], v[68:69], v[100:101]
	v_pk_mul_f32 v[70:71], v[70:71], v[102:103]
	v_pk_mul_f32 v[72:73], v[72:73], v[100:101]
	v_pk_mul_f32 v[74:75], v[74:75], v[102:103]
	v_pk_mul_f32 v[76:77], v[76:77], v[104:105]
	v_pk_mul_f32 v[78:79], v[78:79], v[106:107]
	v_pk_mul_f32 v[80:81], v[80:81], v[104:105]
	v_pk_mul_f32 v[82:83], v[82:83], v[106:107]
	v_pk_mul_f32 v[84:85], v[84:85], v[112:113]
	v_pk_mul_f32 v[86:87], v[86:87], v[114:115]
	v_pk_mul_f32 v[88:89], v[88:89], v[112:113]
	v_pk_mul_f32 v[90:91], v[90:91], v[114:115]
	s_mov_b32 m0, s46
	s_nop 0
	global_load_lds_dwordx4 v255, s[8:9]
	s_add_i32 m0, s46, 0x400
	s_nop 0
	global_load_lds_dwordx4 v254, s[8:9]
	s_mov_b32 m0, s47
	s_nop 0
	global_load_lds_dwordx4 v253, s[10:11]
	s_mov_b32 m0, s48
	s_nop 0
	global_load_lds_dwordx4 v252, s[12:13]
	s_add_i32 m0, s48, 0x400
	s_nop 0
	global_load_lds_dwordx4 v251, s[12:13]
	s_cmp_lt_u32 s33, 29
	s_cselect_b32 s43, 0x10000, 0
	s_add_u32 s8, s8, s43
	s_addc_u32 s9, s9, 0
	s_cmp_lt_u32 s33, 29
	s_cselect_b32 s43, 0x2000, 0
	s_add_u32 s10, s10, s43
	s_addc_u32 s11, s11, 0
	s_cmp_lt_u32 s33, 29
	s_cselect_b32 s43, 0x4000, 0
	s_add_u32 s12, s12, s43
	s_addc_u32 s13, s13, 0
	s_waitcnt lgkmcnt(6)
	v_mfma_f32_16x16x32_bf16 v[60:63], v[12:15], v[44:47], v[60:63]
	v_mfma_f32_16x16x32_bf16 v[64:67], v[12:15], v[48:51], v[64:67]
	v_mfma_f32_16x16x32_bf16 v[68:71], v[16:19], v[44:47], v[68:71]
	v_mfma_f32_16x16x32_bf16 v[72:75], v[16:19], v[48:51], v[72:75]
	v_mfma_f32_16x16x32_bf16 v[76:79], v[20:23], v[44:47], v[76:79]
	v_mfma_f32_16x16x32_bf16 v[80:83], v[20:23], v[48:51], v[80:83]
	v_mfma_f32_16x16x32_bf16 v[84:87], v[24:27], v[44:47], v[84:87]
	v_mfma_f32_16x16x32_bf16 v[88:91], v[24:27], v[48:51], v[88:91]
	s_waitcnt lgkmcnt(0)
	v_mfma_f32_16x16x32_bf16 v[60:63], v[28:31], v[52:55], v[60:63]
	v_mfma_f32_16x16x32_bf16 v[64:67], v[28:31], v[56:59], v[64:67]
	v_mfma_f32_16x16x32_bf16 v[68:71], v[32:35], v[52:55], v[68:71]
	v_mfma_f32_16x16x32_bf16 v[72:75], v[32:35], v[56:59], v[72:75]
	v_mfma_f32_16x16x32_bf16 v[76:79], v[36:39], v[52:55], v[76:79]
	v_mfma_f32_16x16x32_bf16 v[80:83], v[36:39], v[56:59], v[80:83]
	v_mfma_f32_16x16x32_bf16 v[84:87], v[40:43], v[52:55], v[84:87]
	v_mfma_f32_16x16x32_bf16 v[88:91], v[40:43], v[56:59], v[88:91]
	s_nop 3
	global_load_dwordx4 v[108:111], v249, s[16:17]
	s_cmp_lt_u32 s33, 28
	s_cselect_b32 s43, 0x200, 0
	s_add_u32 s16, s16, s43
	s_addc_u32 s17, s17, 0
	s_add_i32 s33, s33, 1
	s_nop 7
	s_nop 7
	v_cvt_pk_bf16_f32 v140, v60, v61
	v_cvt_pk_bf16_f32 v141, v62, v63
	ds_write_b64 v215, v[140:141] offset:0
	v_cvt_pk_bf16_f32 v144, v64, v65
	v_cvt_pk_bf16_f32 v145, v66, v67
	ds_write_b64 v215, v[144:145] offset:4096
	s_nop 1
	v_cvt_pk_bf16_f32 v140, v68, v69
	v_cvt_pk_bf16_f32 v141, v70, v71
	ds_write_b64 v214, v[140:141] offset:0
	v_cvt_pk_bf16_f32 v144, v72, v73
	v_cvt_pk_bf16_f32 v145, v74, v75
	ds_write_b64 v214, v[144:145] offset:4096
	s_nop 1
	v_cvt_pk_bf16_f32 v140, v76, v77
	v_cvt_pk_bf16_f32 v141, v78, v79
	ds_write_b64 v213, v[140:141] offset:0
	v_cvt_pk_bf16_f32 v144, v80, v81
	v_cvt_pk_bf16_f32 v145, v82, v83
	ds_write_b64 v213, v[144:145] offset:4096
	s_nop 1
	v_cvt_pk_bf16_f32 v140, v84, v85
	v_cvt_pk_bf16_f32 v141, v86, v87
	ds_write_b64 v212, v[140:141] offset:0
	v_cvt_pk_bf16_f32 v144, v88, v89
	v_cvt_pk_bf16_f32 v145, v90, v91
	ds_write_b64 v212, v[144:145] offset:4096
	s_nop 1
	s_waitcnt vmcnt(7)
	s_waitcnt lgkmcnt(0)
	s_barrier
; __device__ __forceinline__ void gla_scan_item(const Ctx& C, int item, LAS unsigned char* lds, int tid) {
;     ...
;     float* So = C.out + OUT_GLAP + ((size_t)bh * 128 + wave * 16 + quad * 4) * 256 + sl * 32 + l15;
; #pragma unroll
;     for (int v2 = 0; v2 < 2; ++v2)
; #pragma unroll
;         for (int j = 0; j < 4; ++j) So[(size_t)j * 256 + v2 * 16] = S[v2][j];
;     __syncthreads();
	s_nop 7
	global_store_dword v245, v60, s[34:35] offset:0
	global_store_dword v245, v61, s[34:35] offset:1024
	global_store_dword v245, v62, s[34:35] offset:2048
	global_store_dword v245, v63, s[34:35] offset:3072
	global_store_dword v245, v64, s[34:35] offset:64
	global_store_dword v245, v65, s[34:35] offset:1088
	global_store_dword v245, v66, s[34:35] offset:2112
	global_store_dword v245, v67, s[34:35] offset:3136
	global_store_dword v244, v68, s[34:35] offset:0
	global_store_dword v244, v69, s[34:35] offset:1024
	global_store_dword v244, v70, s[34:35] offset:2048
	global_store_dword v244, v71, s[34:35] offset:3072
	global_store_dword v244, v72, s[34:35] offset:64
	global_store_dword v244, v73, s[34:35] offset:1088
	global_store_dword v244, v74, s[34:35] offset:2112
	global_store_dword v244, v75, s[34:35] offset:3136
	global_store_dword v243, v76, s[34:35] offset:0
	global_store_dword v243, v77, s[34:35] offset:1024
	global_store_dword v243, v78, s[34:35] offset:2048
	global_store_dword v243, v79, s[34:35] offset:3072
	global_store_dword v243, v80, s[34:35] offset:64
	global_store_dword v243, v81, s[34:35] offset:1088
	global_store_dword v243, v82, s[34:35] offset:2112
	global_store_dword v243, v83, s[34:35] offset:3136
	global_store_dword v242, v84, s[34:35] offset:0
	global_store_dword v242, v85, s[34:35] offset:1024
	global_store_dword v242, v86, s[34:35] offset:2048
	global_store_dword v242, v87, s[34:35] offset:3072
	global_store_dword v242, v88, s[34:35] offset:64
	global_store_dword v242, v89, s[34:35] offset:1088
	global_store_dword v242, v90, s[34:35] offset:2112
	global_store_dword v242, v91, s[34:35] offset:3136
	s_waitcnt vmcnt(0) lgkmcnt(0)
	s_barrier
	s_add_i32 s3, s3, s42
	s_cmpk_lt_i32 s3, 0x100
	s_cbranch_scc1 .Lp3S_item
	s_branch .Lp3_done
